# top-k bisection: compare/count body software-pipelined over three SGPR pairs (64 s_nop pads and 32 cndmasks removed per iteration)
# speedup vs baseline: 1.0089x; 1.0089x over previous
; DI void indexer_unit(LAS unsigned char* lds, LAS unsigned long long* smask_w, const bf16_t* PROJ, const bf16_t* KIDXb, const int* posb, int mb0  , int t_0, int njp, int wave, int lane_in) {
;     ...
;         auto wave_total2 = [&](int ca, int cb, int& ta, int& tb) __attribute__((always_inline)) {
;             int x = ca | (cb << 16);
;             x += __builtin_amdgcn_update_dpp(0, x, 0xB1, 0xF, 0xF, true); x += __builtin_amdgcn_update_dpp(0, x, 0x4E, 0xF, 0xF, true);
;             x += __builtin_amdgcn_update_dpp(0, x, 0x141, 0xF, 0xF, true); x += __builtin_amdgcn_update_dpp(0, x, 0x140, 0xF, 0xF, true);
;             const int t = __builtin_amdgcn_readlane(x, 0) + __builtin_amdgcn_readlane(x, 16) + __builtin_amdgcn_readlane(x, 32) + __builtin_amdgcn_readlane(x, 48);
;             ta = t & 0xFFFF; tb = (t >> 16) & 0xFFFF; };
;         int ta, tb; wave_total2(na, nb2, ta, tb);
;         unsigned Ta = 0x00800000u, Tb = 0x00800000u;
;         bool ra = ta > 256, rb = tb > 256;
;         if (ra) Ta = 0u; if (rb) Tb = 0u;
; #pragma unroll 1
;     ...
;             const unsigned ca = Ta | (1u << bit), cb = Tb | (1u << bit); int cnta = 0, cntb = 0;
; #pragma unroll
;             for (int i = 0; i < 32; ++i) { cnta += (ua[i] >= ca) ? 1 : 0; cntb += (ub[i] >= cb) ? 1 : 0; }
;             int wa_, wb_; wave_total2(cnta, cntb, wa_, wb_);
;             if (ra) { if (wa_ >= 256) Ta = ca; if (wa_ == 256) ra = false; }
;             if (rb) { if (wb_ >= 256) Tb = cb; if (wb_ == 256) rb = false; }
;         }
.LBB0_596:
	s_lshl_b32 s0, 1, s96
	s_or_b32 s97, s33, s0
	s_or_b32 s8, s95, s0
	v_mov_b32_e32 v32, 0
	v_mov_b32_e32 v33, 0
	v_cmp_le_u32_e64 s[98:99], s97, v90
	v_cmp_le_u32_e64 s[100:101], s8, v91
	v_cmp_le_u32_e32 vcc, s97, v92
	v_addc_co_u32_e64 v32, s[98:99], 0, v32, s[98:99]
	v_cmp_le_u32_e64 s[98:99], s8, v93
	v_addc_co_u32_e64 v33, s[100:101], 0, v33, s[100:101]
	v_cmp_le_u32_e64 s[100:101], s97, v88
	v_addc_co_u32_e32 v32, vcc, 0, v32, vcc
	v_cmp_le_u32_e32 vcc, s8, v89
	v_addc_co_u32_e64 v33, s[98:99], 0, v33, s[98:99]
	v_cmp_le_u32_e64 s[98:99], s97, v86
	v_addc_co_u32_e64 v32, s[100:101], 0, v32, s[100:101]
	v_cmp_le_u32_e64 s[100:101], s8, v87
	v_addc_co_u32_e32 v33, vcc, 0, v33, vcc
	v_cmp_le_u32_e32 vcc, s97, v84
	v_addc_co_u32_e64 v32, s[98:99], 0, v32, s[98:99]
	v_cmp_le_u32_e64 s[98:99], s8, v85
	v_addc_co_u32_e64 v33, s[100:101], 0, v33, s[100:101]
	v_cmp_le_u32_e64 s[100:101], s97, v82
	v_addc_co_u32_e32 v32, vcc, 0, v32, vcc
	v_cmp_le_u32_e32 vcc, s8, v83
	v_addc_co_u32_e64 v33, s[98:99], 0, v33, s[98:99]
	v_cmp_le_u32_e64 s[98:99], s97, v80
	v_addc_co_u32_e64 v32, s[100:101], 0, v32, s[100:101]
	v_cmp_le_u32_e64 s[100:101], s8, v81
	v_addc_co_u32_e32 v33, vcc, 0, v33, vcc
	v_cmp_le_u32_e32 vcc, s97, v78
	v_addc_co_u32_e64 v32, s[98:99], 0, v32, s[98:99]
	v_cmp_le_u32_e64 s[98:99], s8, v79
	v_addc_co_u32_e64 v33, s[100:101], 0, v33, s[100:101]
	v_cmp_le_u32_e64 s[100:101], s97, v76
	v_addc_co_u32_e32 v32, vcc, 0, v32, vcc
	v_cmp_le_u32_e32 vcc, s8, v77
	v_addc_co_u32_e64 v33, s[98:99], 0, v33, s[98:99]
	v_cmp_le_u32_e64 s[98:99], s97, v74
	v_addc_co_u32_e64 v32, s[100:101], 0, v32, s[100:101]
	v_cmp_le_u32_e64 s[100:101], s8, v75
	v_addc_co_u32_e32 v33, vcc, 0, v33, vcc
	v_cmp_le_u32_e32 vcc, s97, v72
	v_addc_co_u32_e64 v32, s[98:99], 0, v32, s[98:99]
	v_cmp_le_u32_e64 s[98:99], s8, v73
	v_addc_co_u32_e64 v33, s[100:101], 0, v33, s[100:101]
	v_cmp_le_u32_e64 s[100:101], s97, v70
	v_addc_co_u32_e32 v32, vcc, 0, v32, vcc
	v_cmp_le_u32_e32 vcc, s8, v71
	v_addc_co_u32_e64 v33, s[98:99], 0, v33, s[98:99]
	v_cmp_le_u32_e64 s[98:99], s97, v68
	v_addc_co_u32_e64 v32, s[100:101], 0, v32, s[100:101]
	v_cmp_le_u32_e64 s[100:101], s8, v69
	v_addc_co_u32_e32 v33, vcc, 0, v33, vcc
	v_cmp_le_u32_e32 vcc, s97, v66
	v_addc_co_u32_e64 v32, s[98:99], 0, v32, s[98:99]
	v_cmp_le_u32_e64 s[98:99], s8, v67
	v_addc_co_u32_e64 v33, s[100:101], 0, v33, s[100:101]
	v_cmp_le_u32_e64 s[100:101], s97, v64
	v_addc_co_u32_e32 v32, vcc, 0, v32, vcc
	v_cmp_le_u32_e32 vcc, s8, v65
	v_addc_co_u32_e64 v33, s[98:99], 0, v33, s[98:99]
	v_cmp_le_u32_e64 s[98:99], s97, v34
	v_addc_co_u32_e64 v32, s[100:101], 0, v32, s[100:101]
	v_cmp_le_u32_e64 s[100:101], s8, v35
	v_addc_co_u32_e32 v33, vcc, 0, v33, vcc
	v_cmp_le_u32_e32 vcc, s97, v30
	v_addc_co_u32_e64 v32, s[98:99], 0, v32, s[98:99]
	v_cmp_le_u32_e64 s[98:99], s8, v31
	v_addc_co_u32_e64 v33, s[100:101], 0, v33, s[100:101]
	v_cmp_le_u32_e64 s[100:101], s97, v28
	v_addc_co_u32_e32 v32, vcc, 0, v32, vcc
	v_cmp_le_u32_e32 vcc, s8, v29
	v_addc_co_u32_e64 v33, s[98:99], 0, v33, s[98:99]
	v_cmp_le_u32_e64 s[98:99], s97, v26
	v_addc_co_u32_e64 v32, s[100:101], 0, v32, s[100:101]
	v_cmp_le_u32_e64 s[100:101], s8, v27
	v_addc_co_u32_e32 v33, vcc, 0, v33, vcc
	v_cmp_le_u32_e32 vcc, s97, v24
	v_addc_co_u32_e64 v32, s[98:99], 0, v32, s[98:99]
	v_cmp_le_u32_e64 s[98:99], s8, v25
	v_addc_co_u32_e64 v33, s[100:101], 0, v33, s[100:101]
	v_cmp_le_u32_e64 s[100:101], s97, v22
	v_addc_co_u32_e32 v32, vcc, 0, v32, vcc
	v_cmp_le_u32_e32 vcc, s8, v23
	v_addc_co_u32_e64 v33, s[98:99], 0, v33, s[98:99]
	v_cmp_le_u32_e64 s[98:99], s97, v20
	v_addc_co_u32_e64 v32, s[100:101], 0, v32, s[100:101]
	v_cmp_le_u32_e64 s[100:101], s8, v21
	v_addc_co_u32_e32 v33, vcc, 0, v33, vcc
	v_cmp_le_u32_e32 vcc, s97, v18
	v_addc_co_u32_e64 v32, s[98:99], 0, v32, s[98:99]
	v_cmp_le_u32_e64 s[98:99], s8, v19
	v_addc_co_u32_e64 v33, s[100:101], 0, v33, s[100:101]
	v_cmp_le_u32_e64 s[100:101], s97, v16
	v_addc_co_u32_e32 v32, vcc, 0, v32, vcc
	v_cmp_le_u32_e32 vcc, s8, v17
	v_addc_co_u32_e64 v33, s[98:99], 0, v33, s[98:99]
	v_cmp_le_u32_e64 s[98:99], s97, v14
	v_addc_co_u32_e64 v32, s[100:101], 0, v32, s[100:101]
	v_cmp_le_u32_e64 s[100:101], s8, v15
	v_addc_co_u32_e32 v33, vcc, 0, v33, vcc
	v_cmp_le_u32_e32 vcc, s97, v12
	v_addc_co_u32_e64 v32, s[98:99], 0, v32, s[98:99]
	v_cmp_le_u32_e64 s[98:99], s8, v13
	v_addc_co_u32_e64 v33, s[100:101], 0, v33, s[100:101]
	v_cmp_le_u32_e64 s[100:101], s97, v10
	v_addc_co_u32_e32 v32, vcc, 0, v32, vcc
	v_cmp_le_u32_e32 vcc, s8, v11
	v_addc_co_u32_e64 v33, s[98:99], 0, v33, s[98:99]
	v_cmp_le_u32_e64 s[98:99], s97, v8
	v_addc_co_u32_e64 v32, s[100:101], 0, v32, s[100:101]
	v_cmp_le_u32_e64 s[100:101], s8, v9
	v_addc_co_u32_e32 v33, vcc, 0, v33, vcc
	v_cmp_le_u32_e32 vcc, s97, v6
	v_addc_co_u32_e64 v32, s[98:99], 0, v32, s[98:99]
	v_cmp_le_u32_e64 s[98:99], s8, v7
	v_addc_co_u32_e64 v33, s[100:101], 0, v33, s[100:101]
	v_cmp_le_u32_e64 s[100:101], s97, v4
	v_addc_co_u32_e32 v32, vcc, 0, v32, vcc
	v_cmp_le_u32_e32 vcc, s8, v5
	v_addc_co_u32_e64 v33, s[98:99], 0, v33, s[98:99]
	v_cmp_le_u32_e64 s[98:99], s97, v2
	v_addc_co_u32_e64 v32, s[100:101], 0, v32, s[100:101]
	v_cmp_le_u32_e64 s[100:101], s8, v3
	v_addc_co_u32_e32 v33, vcc, 0, v33, vcc
	v_cmp_le_u32_e32 vcc, s97, v0
	v_addc_co_u32_e64 v32, s[98:99], 0, v32, s[98:99]
	v_cmp_le_u32_e64 s[98:99], s8, v1
	v_addc_co_u32_e64 v33, s[100:101], 0, v33, s[100:101]
	v_addc_co_u32_e32 v32, vcc, 0, v32, vcc
	v_addc_co_u32_e64 v33, s[98:99], 0, v33, s[98:99]
	v_lshl_or_b32 v32, v33, 16, v32
	s_nop 1
	v_add_u32_dpp v32, v32, v32 quad_perm:[1,0,3,2] row_mask:0xf bank_mask:0xf bound_ctrl:1
	s_nop 1
	v_add_u32_dpp v32, v32, v32 quad_perm:[2,3,0,1] row_mask:0xf bank_mask:0xf bound_ctrl:1
	s_nop 1
	v_add_u32_dpp v32, v32, v32 row_half_mirror row_mask:0xf bank_mask:0xf bound_ctrl:1
	s_nop 1
	v_add_u32_dpp v32, v32, v32 row_mirror row_mask:0xf bank_mask:0xf bound_ctrl:1
	s_nop 0
	v_readlane_b32 s0, v32, 0
	v_readlane_b32 s1, v32, 16
	s_add_i32 s0, s1, s0
	v_readlane_b32 s1, v32, 32
	s_add_i32 s0, s0, s1
	v_readlane_b32 s1, v32, 48
	s_add_i32 s9, s0, s1
	s_and_b32 s4, s9, 0xffff
	s_cmpk_gt_u32 s4, 0xff
	s_cselect_b64 s[0:1], -1, 0
	s_cmpk_lg_i32 s4, 0x100
	s_cselect_b64 s[4:5], -1, 0
	s_and_b64 s[0:1], s[48:49], s[0:1]
	s_and_b64 s[0:1], s[0:1], exec
	s_cselect_b32 s33, s97, s33
	s_and_b64 s[48:49], s[48:49], s[4:5]
	s_cmp_gt_u32 s9, 0xffffff
	s_cselect_b64 s[0:1], -1, 0
	s_and_b32 s4, s9, 0xffff0000
	s_cmp_lg_u32 s4, 0x1000000
	s_cselect_b64 s[4:5], -1, 0
	s_and_b64 s[0:1], s[50:51], s[0:1]
	s_and_b64 s[0:1], s[0:1], exec
	s_cselect_b32 s95, s8, s95
	s_and_b64 s[50:51], s[50:51], s[4:5]
	v_add_co_u32_e64 v32, s[0:1], s96, -1
	s_or_b64 s[4:5], s[48:49], s[50:51]
	s_and_b64 s[0:1], s[0:1], s[4:5]
	v_readfirstlane_b32 s96, v32
	s_andn2_b64 vcc, exec, s[0:1]
	s_cbranch_vccz .LBB0_596
